# MF=2 DMA GEMM loops: DMA issue over first 4 MFMAs, fragment reads two per MFMA gap over the next 8
# baseline (speedup 1.0000x reference)
; #define MFMA32(a, b, c) __builtin_amdgcn_mfma_f32_32x32x16_bf16((a), (b), (c), 0, 0, 0)
; template <int MF, int BK, class Epi>
; DI void gemm_phase_t(char* lds, const GemmDesc g, const Epi epi) {
;     ...
;     for (int kt = 0; kt < nk; ++kt) {
;       __syncthreads();
;       const u16* sA = sbase + (kt & 1) * STG;
;       const u16* sB = sA + BM * LS;
;       if (kt + 1 < nk) {
;         u16* nA = sbase + ((kt + 1) & 1) * STG;
; #pragma unroll
;         for (int j = 0; j < APT; ++j) *(u32x4*)(nA + (lr + RSTEP * j) * LS + lc * 8) = ra[j];
; #pragma unroll
;         for (int j = 0; j < BPT; ++j) *(u32x4*)(nA + BM * LS + (lr + RSTEP * j) * LS + lc * 8) = rb[j];
;         if (kt + 2 < nk) {
; #pragma unroll
;           for (int j = 0; j < APT; ++j) ra[j] = *(const u32x4*)(Ap + (size_t)j * RSTEP * g.lda + (kt + 2) * BK);
; #pragma unroll
;           for (int j = 0; j < BPT; ++j) rb[j] = *(const u32x4*)(Bp + (size_t)j * RSTEP * g.ldb + (kt + 2) * BK);
;         }
;       }
;       bf16x8 af[NKK][MF], bfr[NKK][2];
; #pragma unroll
;       for (int kk = 0; kk < NKK; ++kk) {
; #pragma unroll
;         for (int ni = 0; ni < 2; ++ni) bfr[kk][ni] = *(const bf16x8*)(sB + (wn * 64 + ni * 32 + l31) * LS + kk * 16 + h * 8);
; #pragma unroll
;         for (int mi = 0; mi < MF; ++mi) af[kk][mi] = *(const bf16x8*)(sA + (wm * (MF * 32) + mi * 32 + l31) * LS + kk * 16 + h * 8);
;       }
;       __builtin_amdgcn_sched_barrier(0);
; #pragma unroll
;       for (int kk = 0; kk < NKK; ++kk)
; #pragma unroll
;         for (int mi = 0; mi < MF; ++mi)
; #pragma unroll
;           for (int ni = 0; ni < 2; ++ni) acc[mi][ni] = MFMA32(bfr[kk][ni], af[kk][mi], acc[mi][ni]);
;     }
.Ldma_dn_loop:
	s_waitcnt vmcnt(0)
	s_waitcnt lgkmcnt(0)
	s_barrier
	v_mfma_f32_32x32x16_bf16 v[52:67], v[68:71], v[76:79], v[52:67]
	s_add_i32 m0, s100, 0x0
	s_nop 0
	global_load_lds_dwordx4 v108, s[12:13]
	s_add_i32 m0, s100, 0x1000
	s_nop 0
	global_load_lds_dwordx4 v109, s[12:13]
	v_mfma_f32_32x32x16_bf16 v[36:51], v[72:75], v[76:79], v[36:51]
	s_add_i32 m0, s100, 0x2000
	s_nop 0
	global_load_lds_dwordx4 v110, s[12:13]
	s_add_i32 m0, s100, 0x3000
	s_nop 0
	global_load_lds_dwordx4 v111, s[12:13]
	v_mfma_f32_32x32x16_bf16 v[20:35], v[68:71], v[80:83], v[20:35]
	s_add_i32 m0, s100, 0x4000
	s_nop 0
	global_load_lds_dwordx4 v108, s[14:15]
	s_add_i32 m0, s100, 0x5000
	s_nop 0
	global_load_lds_dwordx4 v109, s[14:15]
	v_mfma_f32_32x32x16_bf16 v[4:19], v[72:75], v[80:83], v[4:19]
	s_add_i32 m0, s100, 0x6000
	s_nop 0
	global_load_lds_dwordx4 v110, s[14:15]
	s_add_i32 m0, s100, 0x7000
	s_nop 0
	global_load_lds_dwordx4 v111, s[14:15]
	s_add_u32 s12, s12, 0x80
	s_addc_u32 s13, s13, 0
	s_add_u32 s14, s14, 0x80
	s_addc_u32 s15, s15, 0
	v_mfma_f32_32x32x16_bf16 v[52:67], v[84:87], v[92:95], v[52:67]
	ds_read_b128 v[150:153], v234 offset:32768
	ds_read_b128 v[154:157], v234 offset:36864
	v_mfma_f32_32x32x16_bf16 v[36:51], v[88:91], v[92:95], v[36:51]
	ds_read_b128 v[158:161], v114 offset:32768
	ds_read_b128 v[162:165], v114 offset:36864
	v_mfma_f32_32x32x16_bf16 v[20:35], v[84:87], v[96:99], v[20:35]
	ds_read_b128 v[168:171], v235 offset:32768
	ds_read_b128 v[172:175], v235 offset:36864
	v_mfma_f32_32x32x16_bf16 v[4:19], v[88:91], v[96:99], v[4:19]
	ds_read_b128 v[176:179], v115 offset:32768
	ds_read_b128 v[180:183], v115 offset:36864
	v_mfma_f32_32x32x16_bf16 v[52:67], v[118:121], v[126:129], v[52:67]
	ds_read_b128 v[184:187], v236 offset:32768
	ds_read_b128 v[188:191], v236 offset:36864
	v_mfma_f32_32x32x16_bf16 v[36:51], v[122:125], v[126:129], v[36:51]
	ds_read_b128 v[192:195], v116 offset:32768
	ds_read_b128 v[198:201], v116 offset:36864
	v_mfma_f32_32x32x16_bf16 v[20:35], v[118:121], v[130:133], v[20:35]
	ds_read_b128 v[218:221], v237 offset:32768
	ds_read_b128 v[222:225], v237 offset:36864
	v_mfma_f32_32x32x16_bf16 v[4:19], v[122:125], v[130:133], v[4:19]
	ds_read_b128 v[226:229], v117 offset:32768
	ds_read_b128 v[230:233], v117 offset:36864
	v_mfma_f32_32x32x16_bf16 v[52:67], v[134:137], v[142:145], v[52:67]
	v_mfma_f32_32x32x16_bf16 v[36:51], v[138:141], v[142:145], v[36:51]
	v_mfma_f32_32x32x16_bf16 v[20:35], v[134:137], v[146:149], v[20:35]
	v_mfma_f32_32x32x16_bf16 v[4:19], v[138:141], v[146:149], v[4:19]
	s_waitcnt vmcnt(0)
	s_waitcnt lgkmcnt(0)
	s_barrier
	v_mfma_f32_32x32x16_bf16 v[52:67], v[150:153], v[158:161], v[52:67]
	s_add_i32 m0, s100, 0x8000
	s_nop 0
	global_load_lds_dwordx4 v108, s[12:13]
	s_add_i32 m0, s100, 0x9000
	s_nop 0
	global_load_lds_dwordx4 v109, s[12:13]
	v_mfma_f32_32x32x16_bf16 v[36:51], v[154:157], v[158:161], v[36:51]
	s_add_i32 m0, s100, 0xa000
	s_nop 0
	global_load_lds_dwordx4 v110, s[12:13]
	s_add_i32 m0, s100, 0xb000
	s_nop 0
	global_load_lds_dwordx4 v111, s[12:13]
	v_mfma_f32_32x32x16_bf16 v[20:35], v[150:153], v[162:165], v[20:35]
	s_add_i32 m0, s100, 0xc000
	s_nop 0
	global_load_lds_dwordx4 v108, s[14:15]
	s_add_i32 m0, s100, 0xd000
	s_nop 0
	global_load_lds_dwordx4 v109, s[14:15]
	v_mfma_f32_32x32x16_bf16 v[4:19], v[154:157], v[162:165], v[4:19]
	s_add_i32 m0, s100, 0xe000
	s_nop 0
	global_load_lds_dwordx4 v110, s[14:15]
	s_add_i32 m0, s100, 0xf000
	s_nop 0
	global_load_lds_dwordx4 v111, s[14:15]
	s_add_u32 s12, s12, 0x80
	s_addc_u32 s13, s13, 0
	s_add_u32 s14, s14, 0x80
	s_addc_u32 s15, s15, 0
	v_mfma_f32_32x32x16_bf16 v[52:67], v[168:171], v[176:179], v[52:67]
	ds_read_b128 v[68:71], v234
	ds_read_b128 v[72:75], v234 offset:4096
	v_mfma_f32_32x32x16_bf16 v[36:51], v[172:175], v[176:179], v[36:51]
	ds_read_b128 v[76:79], v114
	ds_read_b128 v[80:83], v114 offset:4096
	v_mfma_f32_32x32x16_bf16 v[20:35], v[168:171], v[180:183], v[20:35]
	ds_read_b128 v[84:87], v235
	ds_read_b128 v[88:91], v235 offset:4096
	v_mfma_f32_32x32x16_bf16 v[4:19], v[172:175], v[180:183], v[4:19]
	ds_read_b128 v[92:95], v115
	ds_read_b128 v[96:99], v115 offset:4096
	v_mfma_f32_32x32x16_bf16 v[52:67], v[184:187], v[192:195], v[52:67]
	ds_read_b128 v[118:121], v236
	ds_read_b128 v[122:125], v236 offset:4096
	v_mfma_f32_32x32x16_bf16 v[36:51], v[188:191], v[192:195], v[36:51]
	ds_read_b128 v[126:129], v116
	ds_read_b128 v[130:133], v116 offset:4096
	v_mfma_f32_32x32x16_bf16 v[20:35], v[184:187], v[198:201], v[20:35]
	ds_read_b128 v[134:137], v237
	ds_read_b128 v[138:141], v237 offset:4096
	v_mfma_f32_32x32x16_bf16 v[4:19], v[188:191], v[198:201], v[4:19]
	ds_read_b128 v[142:145], v117
	ds_read_b128 v[146:149], v117 offset:4096
	v_mfma_f32_32x32x16_bf16 v[52:67], v[218:221], v[226:229], v[52:67]
	v_mfma_f32_32x32x16_bf16 v[36:51], v[222:225], v[226:229], v[36:51]
	v_mfma_f32_32x32x16_bf16 v[20:35], v[218:221], v[230:233], v[20:35]
	v_mfma_f32_32x32x16_bf16 v[4:19], v[222:225], v[230:233], v[4:19]
	s_add_i32 s9, s9, -1
	s_cmp_lg_u32 s9, 0
	s_cbranch_scc1 .Ldma_dn_loop
	s_waitcnt vmcnt(0)
	s_waitcnt lgkmcnt(0)
	s_barrier
; #define MFMA32(a, b, c) __builtin_amdgcn_mfma_f32_32x32x16_bf16((a), (b), (c), 0, 0, 0)
; template <int MF, int BK, class Epi>
; DI void gemm_phase_t(char* lds, const GemmDesc g, const Epi epi) {
;     ...
;       __builtin_amdgcn_sched_barrier(0);
; #pragma unroll
;       for (int kk = 0; kk < NKK; ++kk)
; #pragma unroll
;         for (int mi = 0; mi < MF; ++mi)
; #pragma unroll
;           for (int ni = 0; ni < 2; ++ni) acc[mi][ni] = MFMA32(bfr[kk][ni], af[kk][mi], acc[mi][ni]);
;     }
;     epi(acc, g.mbase + m0 + wm * (MF * 32), n0 + wn * 64, l31, h);
;   template <int MF> DI void operator()(f32x16 (&acc)[MF][2], int mb, int nb, int l31, int h) const {
; #pragma unroll
;     for (int mi = 0; mi < MF; ++mi) {
;       const int row = mb + mi * 32 + l31;
;       const float* gr = gate + (size_t)modrow(row) * 6144;
;       const float* rp = row < TL ? res_lat + (size_t)row * D : res_ctx + (size_t)(row - TL) * D;
;       float* op = row < TL ? out_lat + (size_t)row * D : out_ctx + (size_t)(row - TL) * D;
; #pragma unroll
;       for (int g4 = 0; g4 < 4; ++g4)
; #pragma unroll
;         for (int ni = 0; ni < 2; ++ni) {
;           const int col0 = nb + 16 * g4 + 8 * h + 4 * ni;
;           const float4 gt = *(const float4*)(gr + col0);
;           const float4 rv = *(const float4*)(rp + col0);
;           *(float4*)(op + col0) = make_float4(rv.x + gt.x * acc[mi][ni][4 * g4], rv.y + gt.y * acc[mi][ni][4 * g4 + 1], rv.z + gt.z * acc[mi][ni][4 * g4 + 2], rv.w + gt.w * acc[mi][ni][4 * g4 + 3]);
;         }
	v_mfma_f32_32x32x16_bf16 v[52:67], v[68:71], v[76:79], v[52:67]
	ds_read_b128 v[150:153], v234 offset:32768
	ds_read_b128 v[154:157], v234 offset:36864
	v_mfma_f32_32x32x16_bf16 v[36:51], v[72:75], v[76:79], v[36:51]
	ds_read_b128 v[158:161], v114 offset:32768
	ds_read_b128 v[162:165], v114 offset:36864
	v_mfma_f32_32x32x16_bf16 v[20:35], v[68:71], v[80:83], v[20:35]
	ds_read_b128 v[168:171], v235 offset:32768
	ds_read_b128 v[172:175], v235 offset:36864
	v_mfma_f32_32x32x16_bf16 v[4:19], v[72:75], v[80:83], v[4:19]
	ds_read_b128 v[176:179], v115 offset:32768
	ds_read_b128 v[180:183], v115 offset:36864
	v_mfma_f32_32x32x16_bf16 v[52:67], v[84:87], v[92:95], v[52:67]
	ds_read_b128 v[184:187], v236 offset:32768
	ds_read_b128 v[188:191], v236 offset:36864
	v_mfma_f32_32x32x16_bf16 v[36:51], v[88:91], v[92:95], v[36:51]
	ds_read_b128 v[192:195], v116 offset:32768
	ds_read_b128 v[198:201], v116 offset:36864
	v_mfma_f32_32x32x16_bf16 v[20:35], v[84:87], v[96:99], v[20:35]
	ds_read_b128 v[218:221], v237 offset:32768
	ds_read_b128 v[222:225], v237 offset:36864
	v_mfma_f32_32x32x16_bf16 v[4:19], v[88:91], v[96:99], v[4:19]
	ds_read_b128 v[226:229], v117 offset:32768
	ds_read_b128 v[230:233], v117 offset:36864
	v_mfma_f32_32x32x16_bf16 v[52:67], v[118:121], v[126:129], v[52:67]
	v_mfma_f32_32x32x16_bf16 v[36:51], v[122:125], v[126:129], v[36:51]
	v_mfma_f32_32x32x16_bf16 v[20:35], v[118:121], v[130:133], v[20:35]
	v_mfma_f32_32x32x16_bf16 v[4:19], v[122:125], v[130:133], v[4:19]
	v_mfma_f32_32x32x16_bf16 v[52:67], v[134:137], v[142:145], v[52:67]
	v_mfma_f32_32x32x16_bf16 v[36:51], v[138:141], v[142:145], v[36:51]
	v_mfma_f32_32x32x16_bf16 v[20:35], v[134:137], v[146:149], v[20:35]
	v_mfma_f32_32x32x16_bf16 v[4:19], v[138:141], v[146:149], v[4:19]
	s_waitcnt lgkmcnt(0)
	v_mfma_f32_32x32x16_bf16 v[52:67], v[150:153], v[158:161], v[52:67]
	v_mfma_f32_32x32x16_bf16 v[36:51], v[154:157], v[158:161], v[36:51]
	v_mfma_f32_32x32x16_bf16 v[20:35], v[150:153], v[162:165], v[20:35]
	v_mfma_f32_32x32x16_bf16 v[4:19], v[154:157], v[162:165], v[4:19]
	v_mfma_f32_32x32x16_bf16 v[52:67], v[168:171], v[176:179], v[52:67]
	v_mfma_f32_32x32x16_bf16 v[36:51], v[172:175], v[176:179], v[36:51]
	v_mfma_f32_32x32x16_bf16 v[20:35], v[168:171], v[180:183], v[20:35]
	v_mfma_f32_32x32x16_bf16 v[4:19], v[172:175], v[180:183], v[4:19]
	v_mfma_f32_32x32x16_bf16 v[52:67], v[184:187], v[192:195], v[52:67]
	v_mfma_f32_32x32x16_bf16 v[36:51], v[188:191], v[192:195], v[36:51]
	v_mfma_f32_32x32x16_bf16 v[20:35], v[184:187], v[198:201], v[20:35]
	v_mfma_f32_32x32x16_bf16 v[4:19], v[188:191], v[198:201], v[4:19]
	v_mfma_f32_32x32x16_bf16 v[52:67], v[218:221], v[226:229], v[52:67]
	v_mfma_f32_32x32x16_bf16 v[36:51], v[222:225], v[226:229], v[36:51]
	v_mfma_f32_32x32x16_bf16 v[20:35], v[218:221], v[230:233], v[20:35]
	v_mfma_f32_32x32x16_bf16 v[4:19], v[222:225], v[230:233], v[4:19]
	v_or_b32_e32 v68, s8, v113
	v_readlane_b32 s8, v252, 40
	s_add_i32 s6, s6, s8
	s_cmpk_gt_i32 s6, 0x7ff
	v_readlane_b32 s9, v252, 41
	v_mov_b32_e32 v88, s21
	v_mov_b32_e32 v89, s22
	v_mov_b32_e32 v90, s20
	v_add_u32_e32 v86, s7, v112
	v_min_i32_e32 v69, 0x8000, v86
	v_ashrrev_i32_e32 v69, 12, v69
	s_mov_b32 s7, 0x8000
	v_mul_hi_i32_i24_e32 v71, 0x6000, v69
	v_mul_i32_i24_e32 v70, 0x6000, v69
	v_cmp_gt_i32_e32 vcc, s7, v86
	v_add_u32_e32 v69, 0xffff8000, v86
	v_ashrrev_i32_e32 v72, 31, v86
	v_cndmask_b32_e32 v73, 0, v72, vcc
	v_cndmask_b32_e32 v72, v69, v86, vcc
	v_mov_b32_e32 v87, s23
	v_ashrrev_i32_e32 v69, 31, v68
	v_lshl_add_u64 v[70:71], s[2:3], 0, v[70:71]
	v_cndmask_b32_e32 v75, v87, v88, vcc
	v_cndmask_b32_e32 v74, v89, v90, vcc
	v_lshlrev_b64 v[72:73], 12, v[72:73]
	v_lshlrev_b64 v[68:69], 2, v[68:69]
	v_lshl_add_u64 v[72:73], v[74:75], 0, v[72:73]
	v_lshl_add_u64 v[84:85], v[72:73], 0, v[68:69]
	s_movk_i32 s7, 0x7fe0
	v_cmp_gt_i32_e32 vcc, s7, v86
	v_lshl_add_u64 v[82:83], v[70:71], 0, v[68:69]
	s_movk_i32 s7, 0x7fe0
	v_cmp_gt_i32_e32 vcc, s7, v86
	v_or_b32_e32 v76, 32, v86
	v_ashrrev_i32_e32 v72, 31, v76
	v_add_u32_e32 v74, 0xffff8020, v86
	v_cndmask_b32_e32 v73, 0, v72, vcc
	v_cndmask_b32_e32 v72, v74, v76, vcc
	v_cndmask_b32_e32 v75, v87, v88, vcc
	v_cndmask_b32_e32 v74, v89, v90, vcc
	v_lshlrev_b64 v[72:73], 12, v[72:73]
	v_lshl_add_u64 v[72:73], v[74:75], 0, v[72:73]
	v_lshl_add_u64 v[80:81], v[72:73], 0, v[68:69]
	global_load_dwordx4 v[118:121], v[82:83], off
	global_load_dwordx4 v[150:153], v[84:85], off
	global_load_dwordx4 v[122:125], v[82:83], off offset:16
	global_load_dwordx4 v[154:157], v[84:85], off offset:16
	global_load_dwordx4 v[126:129], v[82:83], off offset:64
	global_load_dwordx4 v[158:161], v[84:85], off offset:64
	global_load_dwordx4 v[130:133], v[82:83], off offset:80
	global_load_dwordx4 v[162:165], v[84:85], off offset:80
	global_load_dwordx4 v[134:137], v[82:83], off offset:128
	global_load_dwordx4 v[168:171], v[84:85], off offset:128
	global_load_dwordx4 v[138:141], v[82:83], off offset:144
	global_load_dwordx4 v[172:175], v[84:85], off offset:144
	global_load_dwordx4 v[142:145], v[82:83], off offset:192
	global_load_dwordx4 v[176:179], v[84:85], off offset:192
	global_load_dwordx4 v[146:149], v[82:83], off offset:208
	global_load_dwordx4 v[180:183], v[84:85], off offset:208
	global_load_dwordx4 v[184:187], v[80:81], off
	global_load_dwordx4 v[188:191], v[80:81], off offset:16
	global_load_dwordx4 v[192:195], v[80:81], off offset:64
	global_load_dwordx4 v[198:201], v[80:81], off offset:80
	global_load_dwordx4 v[218:221], v[80:81], off offset:128
	global_load_dwordx4 v[222:225], v[80:81], off offset:144
	global_load_dwordx4 v[226:229], v[80:81], off offset:192
	global_load_dwordx4 v[230:233], v[80:81], off offset:208
	s_waitcnt vmcnt(8)
;   template <int MF> DI void operator()(f32x16 (&acc)[MF][2], int mb, int nb, int l31, int h) const {
;     ...
;       for (int g4 = 0; g4 < 4; ++g4)
; #pragma unroll
;         for (int ni = 0; ni < 2; ++ni) {
;           const int col0 = nb + 16 * g4 + 8 * h + 4 * ni;
;           const float4 gt = *(const float4*)(gr + col0);
;           const float4 rv = *(const float4*)(rp + col0);
;           *(float4*)(op + col0) = make_float4(rv.x + gt.x * acc[mi][ni][4 * g4], rv.y + gt.y * acc[mi][ni][4 * g4 + 1], rv.z + gt.z * acc[mi][ni][4 * g4 + 2], rv.w + gt.w * acc[mi][ni][4 * g4 + 3]);
;         }
	s_nop 4
	v_fma_f32 v52, v52, v118, v150
	v_fma_f32 v53, v53, v119, v151
	v_fma_f32 v54, v54, v120, v152
	v_fma_f32 v55, v55, v121, v153
	global_store_dwordx4 v[84:85], v[52:55], off
	v_fma_f32 v36, v36, v122, v154
	v_fma_f32 v37, v37, v123, v155
	v_fma_f32 v38, v38, v124, v156
	v_fma_f32 v39, v39, v125, v157
	global_store_dwordx4 v[84:85], v[36:39], off offset:16
	v_fma_f32 v56, v56, v126, v158
	v_fma_f32 v57, v57, v127, v159
	v_fma_f32 v58, v58, v128, v160
	v_fma_f32 v59, v59, v129, v161
	global_store_dwordx4 v[84:85], v[56:59], off offset:64
	v_fma_f32 v40, v40, v130, v162
	v_fma_f32 v41, v41, v131, v163
	v_fma_f32 v42, v42, v132, v164
	v_fma_f32 v43, v43, v133, v165
	global_store_dwordx4 v[84:85], v[40:43], off offset:80
	v_fma_f32 v60, v60, v134, v168
	v_fma_f32 v61, v61, v135, v169
	v_fma_f32 v62, v62, v136, v170
	v_fma_f32 v63, v63, v137, v171
	global_store_dwordx4 v[84:85], v[60:63], off offset:128
	v_fma_f32 v44, v44, v138, v172
	v_fma_f32 v45, v45, v139, v173
	v_fma_f32 v46, v46, v140, v174
	v_fma_f32 v47, v47, v141, v175
	global_store_dwordx4 v[84:85], v[44:47], off offset:144
	v_fma_f32 v64, v64, v142, v176
	v_fma_f32 v65, v65, v143, v177
	v_fma_f32 v66, v66, v144, v178
	v_fma_f32 v67, v67, v145, v179
	global_store_dwordx4 v[84:85], v[64:67], off offset:192
	v_fma_f32 v48, v48, v146, v180
	v_fma_f32 v49, v49, v147, v181
	v_fma_f32 v50, v50, v148, v182
	v_fma_f32 v51, v51, v149, v183
	global_store_dwordx4 v[84:85], v[48:51], off offset:208
	s_waitcnt vmcnt(8)
	v_fma_f32 v20, v20, v118, v184
	v_fma_f32 v21, v21, v119, v185
	v_fma_f32 v22, v22, v120, v186
	v_fma_f32 v23, v23, v121, v187
	global_store_dwordx4 v[80:81], v[20:23], off
	v_fma_f32 v4, v4, v122, v188
	v_fma_f32 v5, v5, v123, v189
	v_fma_f32 v6, v6, v124, v190
	v_fma_f32 v7, v7, v125, v191
	global_store_dwordx4 v[80:81], v[4:7], off offset:16
	v_fma_f32 v24, v24, v126, v192
	v_fma_f32 v25, v25, v127, v193
	v_fma_f32 v26, v26, v128, v194
	v_fma_f32 v27, v27, v129, v195
	global_store_dwordx4 v[80:81], v[24:27], off offset:64
	v_fma_f32 v8, v8, v130, v198
	v_fma_f32 v9, v9, v131, v199
	v_fma_f32 v10, v10, v132, v200
	v_fma_f32 v11, v11, v133, v201
	global_store_dwordx4 v[80:81], v[8:11], off offset:80
	v_fma_f32 v28, v28, v134, v218
	v_fma_f32 v29, v29, v135, v219
	v_fma_f32 v30, v30, v136, v220
	v_fma_f32 v31, v31, v137, v221
	global_store_dwordx4 v[80:81], v[28:31], off offset:128
	v_fma_f32 v12, v12, v138, v222
	v_fma_f32 v13, v13, v139, v223
	v_fma_f32 v14, v14, v140, v224
	v_fma_f32 v15, v15, v141, v225
	global_store_dwordx4 v[80:81], v[12:15], off offset:144
	v_fma_f32 v32, v32, v142, v226
	v_fma_f32 v33, v33, v143, v227
	v_fma_f32 v34, v34, v144, v228
	v_fma_f32 v35, v35, v145, v229
	global_store_dwordx4 v[80:81], v[32:35], off offset:192
	v_fma_f32 v16, v16, v146, v230
	v_fma_f32 v17, v17, v147, v231
	v_fma_f32 v18, v18, v148, v232
	v_fma_f32 v19, v19, v149, v233
	global_store_dwordx4 v[80:81], v[16:19], off offset:208
	s_cbranch_scc0 .LBB0_34

; #define MFMA32(a, b, c) __builtin_amdgcn_mfma_f32_32x32x16_bf16((a), (b), (c), 0, 0, 0)
; template <int MF, int BK, class Epi>
; DI void gemm_phase_t(char* lds, const GemmDesc g, const Epi epi) {
;     ...
;     for (int kt = 0; kt < nk; ++kt) {
;       __syncthreads();
;       const u16* sA = sbase + (kt & 1) * STG;
;       const u16* sB = sA + BM * LS;
;       if (kt + 1 < nk) {
;         u16* nA = sbase + ((kt + 1) & 1) * STG;
; #pragma unroll
;         for (int j = 0; j < APT; ++j) *(u32x4*)(nA + (lr + RSTEP * j) * LS + lc * 8) = ra[j];
; #pragma unroll
;         for (int j = 0; j < BPT; ++j) *(u32x4*)(nA + BM * LS + (lr + RSTEP * j) * LS + lc * 8) = rb[j];
;         if (kt + 2 < nk) {
; #pragma unroll
;           for (int j = 0; j < APT; ++j) ra[j] = *(const u32x4*)(Ap + (size_t)j * RSTEP * g.lda + (kt + 2) * BK);
; #pragma unroll
;           for (int j = 0; j < BPT; ++j) rb[j] = *(const u32x4*)(Bp + (size_t)j * RSTEP * g.ldb + (kt + 2) * BK);
;         }
;       }
;       bf16x8 af[NKK][MF], bfr[NKK][2];
; #pragma unroll
;       for (int kk = 0; kk < NKK; ++kk) {
; #pragma unroll
;         for (int ni = 0; ni < 2; ++ni) bfr[kk][ni] = *(const bf16x8*)(sB + (wn * 64 + ni * 32 + l31) * LS + kk * 16 + h * 8);
; #pragma unroll
;         for (int mi = 0; mi < MF; ++mi) af[kk][mi] = *(const bf16x8*)(sA + (wm * (MF * 32) + mi * 32 + l31) * LS + kk * 16 + h * 8);
;       }
;       __builtin_amdgcn_sched_barrier(0);
; #pragma unroll
;       for (int kk = 0; kk < NKK; ++kk)
; #pragma unroll
;         for (int mi = 0; mi < MF; ++mi)
; #pragma unroll
;           for (int ni = 0; ni < 2; ++ni) acc[mi][ni] = MFMA32(bfr[kk][ni], af[kk][mi], acc[mi][ni]);
;     }
.Ldma_op_loop:
	s_waitcnt vmcnt(0)
	s_waitcnt lgkmcnt(0)
	s_barrier
	v_mfma_f32_32x32x16_bf16 v[52:67], v[68:71], v[76:79], v[52:67]
	s_add_i32 m0, s100, 0x0
	s_nop 0
	global_load_lds_dwordx4 v108, s[12:13]
	s_add_i32 m0, s100, 0x1000
	s_nop 0
	global_load_lds_dwordx4 v109, s[12:13]
	v_mfma_f32_32x32x16_bf16 v[36:51], v[72:75], v[76:79], v[36:51]
	s_add_i32 m0, s100, 0x2000
	s_nop 0
	global_load_lds_dwordx4 v110, s[12:13]
	s_add_i32 m0, s100, 0x3000
	s_nop 0
	global_load_lds_dwordx4 v111, s[12:13]
	v_mfma_f32_32x32x16_bf16 v[20:35], v[68:71], v[80:83], v[20:35]
	s_add_i32 m0, s100, 0x4000
	s_nop 0
	global_load_lds_dwordx4 v108, s[14:15]
	s_add_i32 m0, s100, 0x5000
	s_nop 0
	global_load_lds_dwordx4 v109, s[14:15]
	v_mfma_f32_32x32x16_bf16 v[4:19], v[72:75], v[80:83], v[4:19]
	s_add_i32 m0, s100, 0x6000
	s_nop 0
	global_load_lds_dwordx4 v110, s[14:15]
	s_add_i32 m0, s100, 0x7000
	s_nop 0
	global_load_lds_dwordx4 v111, s[14:15]
	s_add_u32 s12, s12, 0x80
	s_addc_u32 s13, s13, 0
	s_add_u32 s14, s14, 0x80
	s_addc_u32 s15, s15, 0
	v_mfma_f32_32x32x16_bf16 v[52:67], v[84:87], v[92:95], v[52:67]
	ds_read_b128 v[150:153], v234 offset:32768
	ds_read_b128 v[154:157], v234 offset:36864
	v_mfma_f32_32x32x16_bf16 v[36:51], v[88:91], v[92:95], v[36:51]
	ds_read_b128 v[158:161], v238 offset:32768
	ds_read_b128 v[162:165], v238 offset:36864
	v_mfma_f32_32x32x16_bf16 v[20:35], v[84:87], v[96:99], v[20:35]
	ds_read_b128 v[168:171], v235 offset:32768
	ds_read_b128 v[172:175], v235 offset:36864
	v_mfma_f32_32x32x16_bf16 v[4:19], v[88:91], v[96:99], v[4:19]
	ds_read_b128 v[176:179], v239 offset:32768
	ds_read_b128 v[180:183], v239 offset:36864
	v_mfma_f32_32x32x16_bf16 v[52:67], v[118:121], v[126:129], v[52:67]
	ds_read_b128 v[184:187], v236 offset:32768
	ds_read_b128 v[188:191], v236 offset:36864
	v_mfma_f32_32x32x16_bf16 v[36:51], v[122:125], v[126:129], v[36:51]
	ds_read_b128 v[192:195], v240 offset:32768
	ds_read_b128 v[198:201], v240 offset:36864
	v_mfma_f32_32x32x16_bf16 v[20:35], v[118:121], v[130:133], v[20:35]
	ds_read_b128 v[218:221], v237 offset:32768
	ds_read_b128 v[222:225], v237 offset:36864
	v_mfma_f32_32x32x16_bf16 v[4:19], v[122:125], v[130:133], v[4:19]
	ds_read_b128 v[226:229], v241 offset:32768
	ds_read_b128 v[230:233], v241 offset:36864
	v_mfma_f32_32x32x16_bf16 v[52:67], v[134:137], v[142:145], v[52:67]
	v_mfma_f32_32x32x16_bf16 v[36:51], v[138:141], v[142:145], v[36:51]
	v_mfma_f32_32x32x16_bf16 v[20:35], v[134:137], v[146:149], v[20:35]
	v_mfma_f32_32x32x16_bf16 v[4:19], v[138:141], v[146:149], v[4:19]
	s_waitcnt vmcnt(0)
	s_waitcnt lgkmcnt(0)
	s_barrier
	v_mfma_f32_32x32x16_bf16 v[52:67], v[150:153], v[158:161], v[52:67]
	s_add_i32 m0, s100, 0x8000
	s_nop 0
	global_load_lds_dwordx4 v108, s[12:13]
	s_add_i32 m0, s100, 0x9000
	s_nop 0
	global_load_lds_dwordx4 v109, s[12:13]
	v_mfma_f32_32x32x16_bf16 v[36:51], v[154:157], v[158:161], v[36:51]
	s_add_i32 m0, s100, 0xa000
	s_nop 0
	global_load_lds_dwordx4 v110, s[12:13]
	s_add_i32 m0, s100, 0xb000
	s_nop 0
	global_load_lds_dwordx4 v111, s[12:13]
	v_mfma_f32_32x32x16_bf16 v[20:35], v[150:153], v[162:165], v[20:35]
	s_add_i32 m0, s100, 0xc000
	s_nop 0
	global_load_lds_dwordx4 v108, s[14:15]
	s_add_i32 m0, s100, 0xd000
	s_nop 0
	global_load_lds_dwordx4 v109, s[14:15]
	v_mfma_f32_32x32x16_bf16 v[4:19], v[154:157], v[162:165], v[4:19]
	s_add_i32 m0, s100, 0xe000
	s_nop 0
	global_load_lds_dwordx4 v110, s[14:15]
	s_add_i32 m0, s100, 0xf000
	s_nop 0
	global_load_lds_dwordx4 v111, s[14:15]
	s_add_u32 s12, s12, 0x80
	s_addc_u32 s13, s13, 0
	s_add_u32 s14, s14, 0x80
	s_addc_u32 s15, s15, 0
	v_mfma_f32_32x32x16_bf16 v[52:67], v[168:171], v[176:179], v[52:67]
	ds_read_b128 v[68:71], v234
	ds_read_b128 v[72:75], v234 offset:4096
	v_mfma_f32_32x32x16_bf16 v[36:51], v[172:175], v[176:179], v[36:51]
	ds_read_b128 v[76:79], v238
	ds_read_b128 v[80:83], v238 offset:4096
	v_mfma_f32_32x32x16_bf16 v[20:35], v[168:171], v[180:183], v[20:35]
	ds_read_b128 v[84:87], v235
	ds_read_b128 v[88:91], v235 offset:4096
	v_mfma_f32_32x32x16_bf16 v[4:19], v[172:175], v[180:183], v[4:19]
	ds_read_b128 v[92:95], v239
	ds_read_b128 v[96:99], v239 offset:4096
	v_mfma_f32_32x32x16_bf16 v[52:67], v[184:187], v[192:195], v[52:67]
	ds_read_b128 v[118:121], v236
	ds_read_b128 v[122:125], v236 offset:4096
	v_mfma_f32_32x32x16_bf16 v[36:51], v[188:191], v[192:195], v[36:51]
	ds_read_b128 v[126:129], v240
	ds_read_b128 v[130:133], v240 offset:4096
	v_mfma_f32_32x32x16_bf16 v[20:35], v[184:187], v[198:201], v[20:35]
	ds_read_b128 v[134:137], v237
	ds_read_b128 v[138:141], v237 offset:4096
	v_mfma_f32_32x32x16_bf16 v[4:19], v[188:191], v[198:201], v[4:19]
	ds_read_b128 v[142:145], v241
	ds_read_b128 v[146:149], v241 offset:4096
	v_mfma_f32_32x32x16_bf16 v[52:67], v[218:221], v[226:229], v[52:67]
	v_mfma_f32_32x32x16_bf16 v[36:51], v[222:225], v[226:229], v[36:51]
	v_mfma_f32_32x32x16_bf16 v[20:35], v[218:221], v[230:233], v[20:35]
	v_mfma_f32_32x32x16_bf16 v[4:19], v[222:225], v[230:233], v[4:19]
	s_add_i32 s9, s9, -1
	s_cmp_lg_u32 s9, 0
	s_cbranch_scc1 .Ldma_op_loop
	s_waitcnt vmcnt(0)
	s_waitcnt lgkmcnt(0)
	s_barrier
; #define MFMA32(a, b, c) __builtin_amdgcn_mfma_f32_32x32x16_bf16((a), (b), (c), 0, 0, 0)
; template <int MF, int BK, class Epi>
; DI void gemm_phase_t(char* lds, const GemmDesc g, const Epi epi) {
;     ...
;       __builtin_amdgcn_sched_barrier(0);
; #pragma unroll
;       for (int kk = 0; kk < NKK; ++kk)
; #pragma unroll
;         for (int mi = 0; mi < MF; ++mi)
; #pragma unroll
;           for (int ni = 0; ni < 2; ++ni) acc[mi][ni] = MFMA32(bfr[kk][ni], af[kk][mi], acc[mi][ni]);
;     }
;     epi(acc, g.mbase + m0 + wm * (MF * 32), n0 + wn * 64, l31, h);
;   template <int MF> DI void operator()(f32x16 (&acc)[MF][2], int mb, int nb, int l31, int h) const {
; #pragma unroll
;     for (int mi = 0; mi < MF; ++mi) {
;       const int row = mb + mi * 32 + l31;
;       const float* gr = gate + (size_t)modrow(row) * 6144;
;       const float* rp = row < TL ? res_lat + (size_t)row * D : res_ctx + (size_t)(row - TL) * D;
;       float* op = row < TL ? out_lat + (size_t)row * D : out_ctx + (size_t)(row - TL) * D;
; #pragma unroll
;       for (int g4 = 0; g4 < 4; ++g4)
; #pragma unroll
;         for (int ni = 0; ni < 2; ++ni) {
;           const int col0 = nb + 16 * g4 + 8 * h + 4 * ni;
;           const float4 gt = *(const float4*)(gr + col0);
;           const float4 rv = *(const float4*)(rp + col0);
;           *(float4*)(op + col0) = make_float4(rv.x + gt.x * acc[mi][ni][4 * g4], rv.y + gt.y * acc[mi][ni][4 * g4 + 1], rv.z + gt.z * acc[mi][ni][4 * g4 + 2], rv.w + gt.w * acc[mi][ni][4 * g4 + 3]);
;         }
	v_mfma_f32_32x32x16_bf16 v[52:67], v[68:71], v[76:79], v[52:67]
	ds_read_b128 v[150:153], v234 offset:32768
	ds_read_b128 v[154:157], v234 offset:36864
	v_mfma_f32_32x32x16_bf16 v[36:51], v[72:75], v[76:79], v[36:51]
	ds_read_b128 v[158:161], v238 offset:32768
	ds_read_b128 v[162:165], v238 offset:36864
	v_mfma_f32_32x32x16_bf16 v[20:35], v[68:71], v[80:83], v[20:35]
	ds_read_b128 v[168:171], v235 offset:32768
	ds_read_b128 v[172:175], v235 offset:36864
	v_mfma_f32_32x32x16_bf16 v[4:19], v[72:75], v[80:83], v[4:19]
	ds_read_b128 v[176:179], v239 offset:32768
	ds_read_b128 v[180:183], v239 offset:36864
	v_mfma_f32_32x32x16_bf16 v[52:67], v[84:87], v[92:95], v[52:67]
	ds_read_b128 v[184:187], v236 offset:32768
	ds_read_b128 v[188:191], v236 offset:36864
	v_mfma_f32_32x32x16_bf16 v[36:51], v[88:91], v[92:95], v[36:51]
	ds_read_b128 v[192:195], v240 offset:32768
	ds_read_b128 v[198:201], v240 offset:36864
	v_mfma_f32_32x32x16_bf16 v[20:35], v[84:87], v[96:99], v[20:35]
	ds_read_b128 v[218:221], v237 offset:32768
	ds_read_b128 v[222:225], v237 offset:36864
	v_mfma_f32_32x32x16_bf16 v[4:19], v[88:91], v[96:99], v[4:19]
	ds_read_b128 v[226:229], v241 offset:32768
	ds_read_b128 v[230:233], v241 offset:36864
	v_mfma_f32_32x32x16_bf16 v[52:67], v[118:121], v[126:129], v[52:67]
	v_mfma_f32_32x32x16_bf16 v[36:51], v[122:125], v[126:129], v[36:51]
	v_mfma_f32_32x32x16_bf16 v[20:35], v[118:121], v[130:133], v[20:35]
	v_mfma_f32_32x32x16_bf16 v[4:19], v[122:125], v[130:133], v[4:19]
	v_mfma_f32_32x32x16_bf16 v[52:67], v[134:137], v[142:145], v[52:67]
	v_mfma_f32_32x32x16_bf16 v[36:51], v[138:141], v[142:145], v[36:51]
	v_mfma_f32_32x32x16_bf16 v[20:35], v[134:137], v[146:149], v[20:35]
	v_mfma_f32_32x32x16_bf16 v[4:19], v[138:141], v[146:149], v[4:19]
	s_waitcnt lgkmcnt(0)
	v_mfma_f32_32x32x16_bf16 v[52:67], v[150:153], v[158:161], v[52:67]
	v_mfma_f32_32x32x16_bf16 v[36:51], v[154:157], v[158:161], v[36:51]
	v_mfma_f32_32x32x16_bf16 v[20:35], v[150:153], v[162:165], v[20:35]
	v_mfma_f32_32x32x16_bf16 v[4:19], v[154:157], v[162:165], v[4:19]
	v_mfma_f32_32x32x16_bf16 v[52:67], v[168:171], v[176:179], v[52:67]
	v_mfma_f32_32x32x16_bf16 v[36:51], v[172:175], v[176:179], v[36:51]
	v_mfma_f32_32x32x16_bf16 v[20:35], v[168:171], v[180:183], v[20:35]
	v_mfma_f32_32x32x16_bf16 v[4:19], v[172:175], v[180:183], v[4:19]
	v_mfma_f32_32x32x16_bf16 v[52:67], v[184:187], v[192:195], v[52:67]
	v_mfma_f32_32x32x16_bf16 v[36:51], v[188:191], v[192:195], v[36:51]
	v_mfma_f32_32x32x16_bf16 v[20:35], v[184:187], v[198:201], v[20:35]
	v_mfma_f32_32x32x16_bf16 v[4:19], v[188:191], v[198:201], v[4:19]
	v_mfma_f32_32x32x16_bf16 v[52:67], v[218:221], v[226:229], v[52:67]
	v_mfma_f32_32x32x16_bf16 v[36:51], v[222:225], v[226:229], v[36:51]
	v_mfma_f32_32x32x16_bf16 v[20:35], v[218:221], v[230:233], v[20:35]
	v_mfma_f32_32x32x16_bf16 v[4:19], v[222:225], v[230:233], v[4:19]
	v_readlane_b32 s10, v253, 26
	v_readlane_b32 s11, v253, 27
	v_or_b32_e32 v68, s7, v114
	v_mov_b32_e32 v88, s10
	v_mov_b32_e32 v89, s31
	v_mov_b32_e32 v90, s29
	v_mov_b32_e32 v91, s30
	v_add_u32_e32 v84, s6, v113
	v_min_i32_e32 v69, 0x8000, v84
	s_mov_b32 s6, 0x8000
	v_ashrrev_i32_e32 v69, 12, v69
	v_cmp_gt_i32_e32 vcc, s6, v84
	v_readlane_b32 s6, v253, 28
	v_mul_hi_i32_i24_e32 v71, 0x6000, v69
	v_mul_i32_i24_e32 v70, 0x6000, v69
	v_add_u32_e32 v69, 0xffff8000, v84
	v_ashrrev_i32_e32 v72, 31, v84
	v_readlane_b32 s7, v253, 29
	v_cndmask_b32_e32 v73, 0, v72, vcc
	v_cndmask_b32_e32 v72, v69, v84, vcc
	v_mov_b32_e32 v85, s7
	v_mov_b32_e32 v86, s11
	v_mov_b32_e32 v87, s6
	v_mov_b32_e32 v92, s28
	v_ashrrev_i32_e32 v69, 31, v68
	v_lshl_add_u64 v[70:71], s[0:1], 0, v[70:71]
	v_cndmask_b32_e32 v75, v85, v86, vcc
	v_cndmask_b32_e32 v74, v87, v88, vcc
	v_lshlrev_b64 v[72:73], 12, v[72:73]
	v_cndmask_b32_e32 v77, v89, v90, vcc
	v_cndmask_b32_e32 v76, v91, v92, vcc
	v_lshlrev_b64 v[68:69], 2, v[68:69]
	v_lshl_add_u64 v[74:75], v[74:75], 0, v[72:73]
	v_lshl_add_u64 v[72:73], v[76:77], 0, v[72:73]
	v_lshl_add_u64 v[78:79], v[70:71], 0, v[68:69]
	v_lshl_add_u64 v[80:81], v[74:75], 0, v[68:69]
	v_lshl_add_u64 v[82:83], v[72:73], 0, v[68:69]
	s_movk_i32 s6, 0x7fe0
	v_cmp_gt_i32_e32 vcc, s6, v84
	v_readlane_b32 s6, v252, 40
	s_add_i32 s8, s8, s6
	s_cmpk_gt_i32 s8, 0x7ff
	v_readlane_b32 s7, v252, 41
	v_or_b32_e32 v76, 32, v84
	v_cndmask_b32_e32 v75, v89, v90, vcc
	v_cndmask_b32_e32 v74, v91, v92, vcc
	v_ashrrev_i32_e32 v70, 31, v76
	v_add_u32_e32 v72, 0xffff8020, v84
	v_cndmask_b32_e32 v71, 0, v70, vcc
	v_cndmask_b32_e32 v70, v72, v76, vcc
	v_cndmask_b32_e32 v73, v85, v86, vcc
	v_cndmask_b32_e32 v72, v87, v88, vcc
	v_lshlrev_b64 v[70:71], 12, v[70:71]
	v_lshl_add_u64 v[72:73], v[72:73], 0, v[70:71]
	v_lshl_add_u64 v[70:71], v[74:75], 0, v[70:71]
	v_lshl_add_u64 v[96:97], v[72:73], 0, v[68:69]
	v_lshl_add_u64 v[98:99], v[70:71], 0, v[68:69]
	global_load_dwordx4 v[118:121], v[78:79], off
	global_load_dwordx4 v[150:153], v[80:81], off
	global_load_dwordx4 v[122:125], v[78:79], off offset:16
	global_load_dwordx4 v[154:157], v[80:81], off offset:16
	global_load_dwordx4 v[126:129], v[78:79], off offset:64
	global_load_dwordx4 v[158:161], v[80:81], off offset:64
	global_load_dwordx4 v[130:133], v[78:79], off offset:80
	global_load_dwordx4 v[162:165], v[80:81], off offset:80
	global_load_dwordx4 v[134:137], v[78:79], off offset:128
	global_load_dwordx4 v[168:171], v[80:81], off offset:128
	global_load_dwordx4 v[138:141], v[78:79], off offset:144
	global_load_dwordx4 v[172:175], v[80:81], off offset:144
	global_load_dwordx4 v[142:145], v[78:79], off offset:192
	global_load_dwordx4 v[176:179], v[80:81], off offset:192
	global_load_dwordx4 v[146:149], v[78:79], off offset:208
	global_load_dwordx4 v[180:183], v[80:81], off offset:208
	global_load_dwordx4 v[184:187], v[96:97], off
	global_load_dwordx4 v[188:191], v[96:97], off offset:16
	global_load_dwordx4 v[192:195], v[96:97], off offset:64
	global_load_dwordx4 v[198:201], v[96:97], off offset:80
	global_load_dwordx4 v[218:221], v[96:97], off offset:128
	global_load_dwordx4 v[222:225], v[96:97], off offset:144
	global_load_dwordx4 v[226:229], v[96:97], off offset:192
	global_load_dwordx4 v[230:233], v[96:97], off offset:208
	s_waitcnt vmcnt(8)
;   template <int MF> DI void operator()(f32x16 (&acc)[MF][2], int mb, int nb, int l31, int h) const {
;     ...
;       for (int g4 = 0; g4 < 4; ++g4)
; #pragma unroll
;         for (int ni = 0; ni < 2; ++ni) {
;           const int col0 = nb + 16 * g4 + 8 * h + 4 * ni;
;           const float4 gt = *(const float4*)(gr + col0);
;           const float4 rv = *(const float4*)(rp + col0);
;           *(float4*)(op + col0) = make_float4(rv.x + gt.x * acc[mi][ni][4 * g4], rv.y + gt.y * acc[mi][ni][4 * g4 + 1], rv.z + gt.z * acc[mi][ni][4 * g4 + 2], rv.w + gt.w * acc[mi][ni][4 * g4 + 3]);
;         }
	s_nop 4
	v_fma_f32 v52, v52, v118, v150
	v_fma_f32 v53, v53, v119, v151
	v_fma_f32 v54, v54, v120, v152
	v_fma_f32 v55, v55, v121, v153
	global_store_dwordx4 v[82:83], v[52:55], off
	v_fma_f32 v36, v36, v122, v154
	v_fma_f32 v37, v37, v123, v155
	v_fma_f32 v38, v38, v124, v156
	v_fma_f32 v39, v39, v125, v157
	global_store_dwordx4 v[82:83], v[36:39], off offset:16
	v_fma_f32 v56, v56, v126, v158
	v_fma_f32 v57, v57, v127, v159
	v_fma_f32 v58, v58, v128, v160
	v_fma_f32 v59, v59, v129, v161
	global_store_dwordx4 v[82:83], v[56:59], off offset:64
	v_fma_f32 v40, v40, v130, v162
	v_fma_f32 v41, v41, v131, v163
	v_fma_f32 v42, v42, v132, v164
	v_fma_f32 v43, v43, v133, v165
	global_store_dwordx4 v[82:83], v[40:43], off offset:80
	v_fma_f32 v60, v60, v134, v168
	v_fma_f32 v61, v61, v135, v169
	v_fma_f32 v62, v62, v136, v170
	v_fma_f32 v63, v63, v137, v171
	global_store_dwordx4 v[82:83], v[60:63], off offset:128
	v_fma_f32 v44, v44, v138, v172
	v_fma_f32 v45, v45, v139, v173
	v_fma_f32 v46, v46, v140, v174
	v_fma_f32 v47, v47, v141, v175
	global_store_dwordx4 v[82:83], v[44:47], off offset:144
	v_fma_f32 v64, v64, v142, v176
	v_fma_f32 v65, v65, v143, v177
	v_fma_f32 v66, v66, v144, v178
	v_fma_f32 v67, v67, v145, v179
	global_store_dwordx4 v[82:83], v[64:67], off offset:192
	v_fma_f32 v48, v48, v146, v180
	v_fma_f32 v49, v49, v147, v181
	v_fma_f32 v50, v50, v148, v182
	v_fma_f32 v51, v51, v149, v183
	global_store_dwordx4 v[82:83], v[48:51], off offset:208
	s_waitcnt vmcnt(8)
	v_fma_f32 v20, v20, v118, v184
	v_fma_f32 v21, v21, v119, v185
	v_fma_f32 v22, v22, v120, v186
	v_fma_f32 v23, v23, v121, v187
	global_store_dwordx4 v[98:99], v[20:23], off
	v_fma_f32 v4, v4, v122, v188
	v_fma_f32 v5, v5, v123, v189
	v_fma_f32 v6, v6, v124, v190
	v_fma_f32 v7, v7, v125, v191
	global_store_dwordx4 v[98:99], v[4:7], off offset:16
	v_fma_f32 v24, v24, v126, v192
	v_fma_f32 v25, v25, v127, v193
	v_fma_f32 v26, v26, v128, v194
	v_fma_f32 v27, v27, v129, v195
	global_store_dwordx4 v[98:99], v[24:27], off offset:64
	v_fma_f32 v8, v8, v130, v198
	v_fma_f32 v9, v9, v131, v199
	v_fma_f32 v10, v10, v132, v200
	v_fma_f32 v11, v11, v133, v201
	global_store_dwordx4 v[98:99], v[8:11], off offset:80
	v_fma_f32 v28, v28, v134, v218
	v_fma_f32 v29, v29, v135, v219
	v_fma_f32 v30, v30, v136, v220
	v_fma_f32 v31, v31, v137, v221
	global_store_dwordx4 v[98:99], v[28:31], off offset:128
	v_fma_f32 v12, v12, v138, v222
	v_fma_f32 v13, v13, v139, v223
	v_fma_f32 v14, v14, v140, v224
	v_fma_f32 v15, v15, v141, v225
	global_store_dwordx4 v[98:99], v[12:15], off offset:144
	v_fma_f32 v32, v32, v142, v226
	v_fma_f32 v33, v33, v143, v227
	v_fma_f32 v34, v34, v144, v228
	v_fma_f32 v35, v35, v145, v229
	global_store_dwordx4 v[98:99], v[32:35], off offset:192
	v_fma_f32 v16, v16, v146, v230
	v_fma_f32 v17, v17, v147, v231
	v_fma_f32 v18, v18, v148, v232
	v_fma_f32 v19, v19, v149, v233
	global_store_dwordx4 v[98:99], v[16:19], off offset:208
	s_cbranch_scc0 .LBB0_305

; #define MFMA32(a, b, c) __builtin_amdgcn_mfma_f32_32x32x16_bf16((a), (b), (c), 0, 0, 0)
; template <int MF, int BK, class Epi>
; DI void gemm_phase_t(char* lds, const GemmDesc g, const Epi epi) {
;     ...
;     for (int kt = 0; kt < nk; ++kt) {
;       __syncthreads();
;       const u16* sA = sbase + (kt & 1) * STG;
;       const u16* sB = sA + BM * LS;
;       if (kt + 1 < nk) {
;         u16* nA = sbase + ((kt + 1) & 1) * STG;
; #pragma unroll
;         for (int j = 0; j < APT; ++j) *(u32x4*)(nA + (lr + RSTEP * j) * LS + lc * 8) = ra[j];
; #pragma unroll
;         for (int j = 0; j < BPT; ++j) *(u32x4*)(nA + BM * LS + (lr + RSTEP * j) * LS + lc * 8) = rb[j];
;         if (kt + 2 < nk) {
; #pragma unroll
;           for (int j = 0; j < APT; ++j) ra[j] = *(const u32x4*)(Ap + (size_t)j * RSTEP * g.lda + (kt + 2) * BK);
; #pragma unroll
;           for (int j = 0; j < BPT; ++j) rb[j] = *(const u32x4*)(Bp + (size_t)j * RSTEP * g.ldb + (kt + 2) * BK);
;         }
;       }
;       bf16x8 af[NKK][MF], bfr[NKK][2];
; #pragma unroll
;       for (int kk = 0; kk < NKK; ++kk) {
; #pragma unroll
;         for (int ni = 0; ni < 2; ++ni) bfr[kk][ni] = *(const bf16x8*)(sB + (wn * 64 + ni * 32 + l31) * LS + kk * 16 + h * 8);
; #pragma unroll
;         for (int mi = 0; mi < MF; ++mi) af[kk][mi] = *(const bf16x8*)(sA + (wm * (MF * 32) + mi * 32 + l31) * LS + kk * 16 + h * 8);
;       }
;       __builtin_amdgcn_sched_barrier(0);
; #pragma unroll
;       for (int kk = 0; kk < NKK; ++kk)
; #pragma unroll
;         for (int mi = 0; mi < MF; ++mi)
; #pragma unroll
;           for (int ni = 0; ni < 2; ++ni) acc[mi][ni] = MFMA32(bfr[kk][ni], af[kk][mi], acc[mi][ni]);
;     }
.Ldma_oi_loop:
	s_waitcnt vmcnt(0)
	s_waitcnt lgkmcnt(0)
	s_barrier
	v_mfma_f32_32x32x16_bf16 v[52:67], v[102:105], v[110:113], v[52:67]
	s_add_i32 m0, s3, 0x0
	s_nop 0
	global_load_lds_dwordx4 v68, s[98:99]
	s_add_i32 m0, s3, 0x1000
	s_nop 0
	global_load_lds_dwordx4 v69, s[98:99]
	v_mfma_f32_32x32x16_bf16 v[36:51], v[106:109], v[110:113], v[36:51]
	s_add_i32 m0, s3, 0x2000
	s_nop 0
	global_load_lds_dwordx4 v70, s[98:99]
	s_add_i32 m0, s3, 0x3000
	s_nop 0
	global_load_lds_dwordx4 v71, s[98:99]
	v_mfma_f32_32x32x16_bf16 v[20:35], v[102:105], v[114:117], v[20:35]
	s_add_i32 m0, s3, 0x4000
	s_nop 0
	global_load_lds_dwordx4 v68, s[100:101]
	s_add_i32 m0, s3, 0x5000
	s_nop 0
	global_load_lds_dwordx4 v69, s[100:101]
	v_mfma_f32_32x32x16_bf16 v[4:19], v[106:109], v[114:117], v[4:19]
	s_add_i32 m0, s3, 0x6000
	s_nop 0
	global_load_lds_dwordx4 v70, s[100:101]
	s_add_i32 m0, s3, 0x7000
	s_nop 0
	global_load_lds_dwordx4 v71, s[100:101]
	s_add_u32 s98, s98, 0x80
	s_addc_u32 s99, s99, 0
	s_add_u32 s100, s100, 0x80
	s_addc_u32 s101, s101, 0
	v_mfma_f32_32x32x16_bf16 v[52:67], v[118:121], v[126:129], v[52:67]
	ds_read_b128 v[168:171], v238 offset:32768
	ds_read_b128 v[172:175], v238 offset:36864
	v_mfma_f32_32x32x16_bf16 v[36:51], v[122:125], v[126:129], v[36:51]
	ds_read_b128 v[176:179], v80 offset:32768
	ds_read_b128 v[180:183], v80 offset:36864
	v_mfma_f32_32x32x16_bf16 v[20:35], v[118:121], v[130:133], v[20:35]
	ds_read_b128 v[184:187], v239 offset:32768
	ds_read_b128 v[188:191], v239 offset:36864
	v_mfma_f32_32x32x16_bf16 v[4:19], v[122:125], v[130:133], v[4:19]
	ds_read_b128 v[192:195], v81 offset:32768
	ds_read_b128 v[204:207], v81 offset:36864
	v_mfma_f32_32x32x16_bf16 v[52:67], v[134:137], v[142:145], v[52:67]
	ds_read_b128 v[82:85], v240 offset:32768
	ds_read_b128 v[86:89], v240 offset:36864
	v_mfma_f32_32x32x16_bf16 v[36:51], v[138:141], v[142:145], v[36:51]
	ds_read_b128 v[90:93], v98 offset:32768
	ds_read_b128 v[218:221], v98 offset:36864
	v_mfma_f32_32x32x16_bf16 v[20:35], v[134:137], v[146:149], v[20:35]
	ds_read_b128 v[222:225], v241 offset:32768
	ds_read_b128 v[226:229], v241 offset:36864
	v_mfma_f32_32x32x16_bf16 v[4:19], v[138:141], v[146:149], v[4:19]
	ds_read_b128 v[230:233], v100 offset:32768
	ds_read_b128 v[234:237], v100 offset:36864
	v_mfma_f32_32x32x16_bf16 v[52:67], v[150:153], v[158:161], v[52:67]
	v_mfma_f32_32x32x16_bf16 v[36:51], v[154:157], v[158:161], v[36:51]
	v_mfma_f32_32x32x16_bf16 v[20:35], v[150:153], v[162:165], v[20:35]
	v_mfma_f32_32x32x16_bf16 v[4:19], v[154:157], v[162:165], v[4:19]
	s_waitcnt vmcnt(0)
	s_waitcnt lgkmcnt(0)
	s_barrier
	v_mfma_f32_32x32x16_bf16 v[52:67], v[168:171], v[176:179], v[52:67]
	s_add_i32 m0, s3, 0x8000
	s_nop 0
	global_load_lds_dwordx4 v68, s[98:99]
	s_add_i32 m0, s3, 0x9000
	s_nop 0
	global_load_lds_dwordx4 v69, s[98:99]
	v_mfma_f32_32x32x16_bf16 v[36:51], v[172:175], v[176:179], v[36:51]
	s_add_i32 m0, s3, 0xa000
	s_nop 0
	global_load_lds_dwordx4 v70, s[98:99]
	s_add_i32 m0, s3, 0xb000
	s_nop 0
	global_load_lds_dwordx4 v71, s[98:99]
	v_mfma_f32_32x32x16_bf16 v[20:35], v[168:171], v[180:183], v[20:35]
	s_add_i32 m0, s3, 0xc000
	s_nop 0
	global_load_lds_dwordx4 v68, s[100:101]
	s_add_i32 m0, s3, 0xd000
	s_nop 0
	global_load_lds_dwordx4 v69, s[100:101]
	v_mfma_f32_32x32x16_bf16 v[4:19], v[172:175], v[180:183], v[4:19]
	s_add_i32 m0, s3, 0xe000
	s_nop 0
	global_load_lds_dwordx4 v70, s[100:101]
	s_add_i32 m0, s3, 0xf000
	s_nop 0
	global_load_lds_dwordx4 v71, s[100:101]
	s_add_u32 s98, s98, 0x80
	s_addc_u32 s99, s99, 0
	s_add_u32 s100, s100, 0x80
	s_addc_u32 s101, s101, 0
	v_mfma_f32_32x32x16_bf16 v[52:67], v[184:187], v[192:195], v[52:67]
	ds_read_b128 v[102:105], v238
	ds_read_b128 v[106:109], v238 offset:4096
	v_mfma_f32_32x32x16_bf16 v[36:51], v[188:191], v[192:195], v[36:51]
	ds_read_b128 v[110:113], v80
	ds_read_b128 v[114:117], v80 offset:4096
	v_mfma_f32_32x32x16_bf16 v[20:35], v[184:187], v[204:207], v[20:35]
	ds_read_b128 v[118:121], v239
	ds_read_b128 v[122:125], v239 offset:4096
	v_mfma_f32_32x32x16_bf16 v[4:19], v[188:191], v[204:207], v[4:19]
	ds_read_b128 v[126:129], v81
	ds_read_b128 v[130:133], v81 offset:4096
	v_mfma_f32_32x32x16_bf16 v[52:67], v[82:85], v[90:93], v[52:67]
	ds_read_b128 v[134:137], v240
	ds_read_b128 v[138:141], v240 offset:4096
	v_mfma_f32_32x32x16_bf16 v[36:51], v[86:89], v[90:93], v[36:51]
	ds_read_b128 v[142:145], v98
	ds_read_b128 v[146:149], v98 offset:4096
	v_mfma_f32_32x32x16_bf16 v[20:35], v[82:85], v[218:221], v[20:35]
	ds_read_b128 v[150:153], v241
	ds_read_b128 v[154:157], v241 offset:4096
	v_mfma_f32_32x32x16_bf16 v[4:19], v[86:89], v[218:221], v[4:19]
	ds_read_b128 v[158:161], v100
	ds_read_b128 v[162:165], v100 offset:4096
	v_mfma_f32_32x32x16_bf16 v[52:67], v[222:225], v[230:233], v[52:67]
	v_mfma_f32_32x32x16_bf16 v[36:51], v[226:229], v[230:233], v[36:51]
	v_mfma_f32_32x32x16_bf16 v[20:35], v[222:225], v[234:237], v[20:35]
	v_mfma_f32_32x32x16_bf16 v[4:19], v[226:229], v[234:237], v[4:19]
	s_add_i32 s2, s2, -1
	s_cmp_lg_u32 s2, 0
	s_cbranch_scc1 .Ldma_oi_loop
	s_waitcnt vmcnt(0)
	s_waitcnt lgkmcnt(0)
	s_barrier
; #define MFMA32(a, b, c) __builtin_amdgcn_mfma_f32_32x32x16_bf16((a), (b), (c), 0, 0, 0)
; template <int MF, int BK, class Epi>
; DI void gemm_phase_t(char* lds, const GemmDesc g, const Epi epi) {
;     ...
;       __builtin_amdgcn_sched_barrier(0);
; #pragma unroll
;       for (int kk = 0; kk < NKK; ++kk)
; #pragma unroll
;         for (int mi = 0; mi < MF; ++mi)
; #pragma unroll
;           for (int ni = 0; ni < 2; ++ni) acc[mi][ni] = MFMA32(bfr[kk][ni], af[kk][mi], acc[mi][ni]);
;     }
;     epi(acc, g.mbase + m0 + wm * (MF * 32), n0 + wn * 64, l31, h);
;   template <int MF> DI void operator()(f32x16 (&acc)[MF][2], int mb, int nb, int l31, int h) const {
;     ...
;     const int which = nb >> 9, head = ((nb >> 6) & 1) * 4 + ((nb >> 7) & 3);
; #pragma unroll
;     for (int mi = 0; mi < MF; ++mi) {
;       const int row = mb + mi * 32 + l31;
;       const bool isl = row < TL;
;       const int b = isl ? row >> 12 : (row - TL) >> 8;
;       const int t = isl ? row & 4095 : (row - TL) & 255;
;       float x[4][8];
; #pragma unroll
;       for (int g4 = 0; g4 < 4; ++g4)
; #pragma unroll
;         for (int k = 0; k < 4; ++k) { x[g4][k] = acc[mi][0][4 * g4 + k]; x[g4][4 + k] = acc[mi][1][4 * g4 + k]; }
;       if (isl) {
;         const float* sr = rope + (t >> 6) * 16 + 8 * h; const float* sc = rope + (t & 63) * 16 + 8 * h;
;         const float4 s1a = *(const float4*)(sr), s1b = *(const float4*)(sr + 4), c1a = *(const float4*)(sr + 1024), c1b = *(const float4*)(sr + 1028);
;         const float4 s2a = *(const float4*)(sc), s2b = *(const float4*)(sc + 4), c2a = *(const float4*)(sc + 1024), c2b = *(const float4*)(sc + 1028);
;         const float s1[8] = {s1a.x, s1a.y, s1a.z, s1a.w, s1b.x, s1b.y, s1b.z, s1b.w}, c1[8] = {c1a.x, c1a.y, c1a.z, c1a.w, c1b.x, c1b.y, c1b.z, c1b.w};
;         const float s2[8] = {s2a.x, s2a.y, s2a.z, s2a.w, s2b.x, s2b.y, s2b.z, s2b.w}, c2[8] = {c2a.x, c2a.y, c2a.z, c2a.w, c2b.x, c2b.y, c2b.z, c2b.w};
; #pragma unroll
;         for (int k = 0; k < 8; ++k) {
;           const float a = x[0][k], bq = x[1][k], cq = x[2][k], dq = x[3][k];
;           x[0][k] = a * c1[k] - bq * s1[k]; x[1][k] = bq * c1[k] + a * s1[k];
;           x[2][k] = cq * c2[k] - dq * s2[k]; x[3][k] = dq * c2[k] + cq * s2[k];
;         }
	v_mfma_f32_32x32x16_bf16 v[52:67], v[102:105], v[110:113], v[52:67]
	ds_read_b128 v[168:171], v238 offset:32768
	ds_read_b128 v[172:175], v238 offset:36864
	v_mfma_f32_32x32x16_bf16 v[36:51], v[106:109], v[110:113], v[36:51]
	ds_read_b128 v[176:179], v80 offset:32768
	ds_read_b128 v[180:183], v80 offset:36864
	v_mfma_f32_32x32x16_bf16 v[20:35], v[102:105], v[114:117], v[20:35]
	ds_read_b128 v[184:187], v239 offset:32768
	ds_read_b128 v[188:191], v239 offset:36864
	v_mfma_f32_32x32x16_bf16 v[4:19], v[106:109], v[114:117], v[4:19]
	ds_read_b128 v[192:195], v81 offset:32768
	ds_read_b128 v[204:207], v81 offset:36864
	v_mfma_f32_32x32x16_bf16 v[52:67], v[118:121], v[126:129], v[52:67]
	ds_read_b128 v[82:85], v240 offset:32768
	ds_read_b128 v[86:89], v240 offset:36864
	v_mfma_f32_32x32x16_bf16 v[36:51], v[122:125], v[126:129], v[36:51]
	ds_read_b128 v[90:93], v98 offset:32768
	ds_read_b128 v[218:221], v98 offset:36864
	v_mfma_f32_32x32x16_bf16 v[20:35], v[118:121], v[130:133], v[20:35]
	ds_read_b128 v[222:225], v241 offset:32768
	ds_read_b128 v[226:229], v241 offset:36864
	v_mfma_f32_32x32x16_bf16 v[4:19], v[122:125], v[130:133], v[4:19]
	ds_read_b128 v[230:233], v100 offset:32768
	ds_read_b128 v[234:237], v100 offset:36864
	v_mfma_f32_32x32x16_bf16 v[52:67], v[134:137], v[142:145], v[52:67]
	v_mfma_f32_32x32x16_bf16 v[36:51], v[138:141], v[142:145], v[36:51]
	v_mfma_f32_32x32x16_bf16 v[20:35], v[134:137], v[146:149], v[20:35]
	v_mfma_f32_32x32x16_bf16 v[4:19], v[138:141], v[146:149], v[4:19]
	v_mfma_f32_32x32x16_bf16 v[52:67], v[150:153], v[158:161], v[52:67]
	v_mfma_f32_32x32x16_bf16 v[36:51], v[154:157], v[158:161], v[36:51]
	v_mfma_f32_32x32x16_bf16 v[20:35], v[150:153], v[162:165], v[20:35]
	v_mfma_f32_32x32x16_bf16 v[4:19], v[154:157], v[162:165], v[4:19]
	s_waitcnt lgkmcnt(0)
	v_mfma_f32_32x32x16_bf16 v[52:67], v[168:171], v[176:179], v[52:67]
	v_mfma_f32_32x32x16_bf16 v[36:51], v[172:175], v[176:179], v[36:51]
	v_mfma_f32_32x32x16_bf16 v[20:35], v[168:171], v[180:183], v[20:35]
	v_mfma_f32_32x32x16_bf16 v[4:19], v[172:175], v[180:183], v[4:19]
	v_mfma_f32_32x32x16_bf16 v[52:67], v[184:187], v[192:195], v[52:67]
	v_mfma_f32_32x32x16_bf16 v[36:51], v[188:191], v[192:195], v[36:51]
	v_mfma_f32_32x32x16_bf16 v[20:35], v[184:187], v[204:207], v[20:35]
	v_mfma_f32_32x32x16_bf16 v[4:19], v[188:191], v[204:207], v[4:19]
	v_mfma_f32_32x32x16_bf16 v[52:67], v[82:85], v[90:93], v[52:67]
	v_mfma_f32_32x32x16_bf16 v[36:51], v[86:89], v[90:93], v[36:51]
	v_mfma_f32_32x32x16_bf16 v[20:35], v[82:85], v[218:221], v[20:35]
	v_mfma_f32_32x32x16_bf16 v[4:19], v[86:89], v[218:221], v[4:19]
	v_mfma_f32_32x32x16_bf16 v[52:67], v[222:225], v[230:233], v[52:67]
	v_mfma_f32_32x32x16_bf16 v[36:51], v[226:229], v[230:233], v[36:51]
	v_mfma_f32_32x32x16_bf16 v[20:35], v[222:225], v[234:237], v[20:35]
	v_mfma_f32_32x32x16_bf16 v[4:19], v[226:229], v[234:237], v[4:19]
	v_add_u32_e32 v70, s21, v95
	v_add_u32_e32 v89, s0, v96
	s_movk_i32 s0, 0x400
	v_cmp_gt_i32_e32 vcc, s0, v70
	v_or_b32_e32 v88, v89, v77
	s_and_saveexec_b64 s[0:1], vcc
	s_xor_b64 s[12:13], exec, s[0:1]
	s_cbranch_execz .LBB0_932
	s_movk_i32 s0, 0x7fff
	s_mov_b32 s2, 0x8000
	s_movk_i32 s14, 0xfdf
	v_cmp_lt_i32_e64 s[0:1], s0, v88
	v_cmp_gt_i32_e64 s[2:3], s2, v88
	v_bitop3_b32 v90, v89, s14, v77 bitop3:0xc8
	v_and_b32_e32 v82, 0xfc0, v89
	s_and_saveexec_b64 s[14:15], s[2:3]
	s_cbranch_execz .LBB0_913
	v_lshlrev_b32_e32 v2, 6, v90
	v_mov_b32_e32 v83, v3
	v_and_b32_e32 v2, 0x7c0, v2
	v_lshl_add_u64 v[68:69], v[78:79], 0, v[82:83]
	v_lshl_add_u64 v[86:87], v[78:79], 0, v[2:3]
	s_mov_b64 s[16:17], 0x1000
	v_lshl_add_u64 v[70:71], v[68:69], 0, s[16:17]
	v_lshl_add_u64 v[92:93], v[86:87], 0, s[16:17]
	s_movk_i32 s16, 0x1000
	global_load_dwordx4 v[102:105], v[68:69], off offset:16
	global_load_dwordx4 v[106:109], v[68:69], off
	v_add_co_u32_e32 v68, vcc, s16, v68
	s_nop 1
	v_addc_co_u32_e32 v69, vcc, 0, v69, vcc
	global_load_dwordx4 v[110:113], v[68:69], off
	global_load_dwordx4 v[114:117], v[70:71], off offset:16
	s_waitcnt vmcnt(2)
	v_pk_mul_f32 v[68:69], v[56:57], v[106:107]
	s_waitcnt vmcnt(1)
	v_pk_mul_f32 v[56:57], v[56:57], v[110:111]
	v_pk_fma_f32 v[84:85], v[52:53], v[110:111], v[68:69] neg_lo:[0,0,1] neg_hi:[0,0,1]
	v_pk_fma_f32 v[56:57], v[52:53], v[106:107], v[56:57]
	global_load_dwordx4 v[68:71], v[86:87], off offset:16
	global_load_dwordx4 v[118:121], v[86:87], off
	v_add_co_u32_e32 v52, vcc, s16, v86
	s_nop 1
	v_addc_co_u32_e32 v53, vcc, 0, v87, vcc
	global_load_dwordx4 v[122:125], v[52:53], off
	global_load_dwordx4 v[126:129], v[92:93], off offset:16
	s_waitcnt vmcnt(2)
	v_pk_mul_f32 v[52:53], v[64:65], v[118:119]
	s_waitcnt vmcnt(1)
	v_pk_fma_f32 v[86:87], v[60:61], v[122:123], v[52:53] neg_lo:[0,0,1] neg_hi:[0,0,1]
	v_pk_mul_f32 v[52:53], v[64:65], v[122:123]
	s_nop 0
	v_pk_fma_f32 v[64:65], v[60:61], v[118:119], v[52:53]
	v_pk_mul_f32 v[52:53], v[58:59], v[108:109]
	v_pk_mul_f32 v[58:59], v[58:59], v[112:113]
	v_pk_fma_f32 v[52:53], v[54:55], v[112:113], v[52:53] neg_lo:[0,0,1] neg_hi:[0,0,1]
	v_pk_fma_f32 v[58:59], v[54:55], v[108:109], v[58:59]
	v_pk_mul_f32 v[54:55], v[66:67], v[120:121]
	s_nop 0
	v_pk_fma_f32 v[60:61], v[62:63], v[124:125], v[54:55] neg_lo:[0,0,1] neg_hi:[0,0,1]
	v_pk_mul_f32 v[54:55], v[66:67], v[124:125]
	s_nop 0
	v_pk_fma_f32 v[66:67], v[62:63], v[120:121], v[54:55]
	v_pk_mul_f32 v[54:55], v[40:41], v[102:103]
	v_pk_mul_f32 v[40:41], v[40:41], v[114:115]
	v_pk_fma_f32 v[54:55], v[36:37], v[114:115], v[54:55] neg_lo:[0,0,1] neg_hi:[0,0,1]
	v_pk_fma_f32 v[40:41], v[36:37], v[102:103], v[40:41]
	v_pk_mul_f32 v[36:37], v[48:49], v[68:69]
	s_waitcnt vmcnt(0)
	v_pk_fma_f32 v[62:63], v[44:45], v[126:127], v[36:37] neg_lo:[0,0,1] neg_hi:[0,0,1]
	v_pk_mul_f32 v[36:37], v[48:49], v[126:127]
	s_nop 0
	v_pk_fma_f32 v[48:49], v[44:45], v[68:69], v[36:37]
	v_pk_mul_f32 v[36:37], v[42:43], v[104:105]
	v_pk_mul_f32 v[42:43], v[42:43], v[116:117]
	v_pk_fma_f32 v[36:37], v[38:39], v[116:117], v[36:37] neg_lo:[0,0,1] neg_hi:[0,0,1]
	v_pk_fma_f32 v[42:43], v[38:39], v[104:105], v[42:43]
	v_pk_mul_f32 v[38:39], v[50:51], v[70:71]
	s_nop 0
	v_pk_fma_f32 v[44:45], v[46:47], v[128:129], v[38:39] neg_lo:[0,0,1] neg_hi:[0,0,1]
	v_pk_mul_f32 v[38:39], v[50:51], v[128:129]
	s_nop 0
	v_pk_fma_f32 v[50:51], v[46:47], v[70:71], v[38:39]
	v_mov_b32_e32 v38, v36
	v_mov_b32_e32 v39, v37
	v_mov_b32_e32 v36, v54
	v_mov_b32_e32 v37, v55
	v_mov_b32_e32 v54, v52
	v_mov_b32_e32 v55, v53
	v_mov_b32_e32 v52, v84
	v_mov_b32_e32 v53, v85
	v_mov_b32_e32 v46, v44
	v_mov_b32_e32 v47, v45
	v_mov_b32_e32 v44, v62
	v_mov_b32_e32 v45, v63
	v_mov_b32_e32 v62, v60
	v_mov_b32_e32 v63, v61
	v_mov_b32_e32 v60, v86
	v_mov_b32_e32 v61, v87
